# grid barrier: XCD leader issues its buffer_inv sc1 right after its write-back completes (overlaps cross-XCD arrival) instead of before the local release
# speedup vs baseline: 1.0052x; 1.0020x over previous
; __device__ __forceinline__ unsigned xb_ld(unsigned* p)              { return __hip_atomic_load(p, __ATOMIC_RELAXED, __HIP_MEMORY_SCOPE_AGENT); }
; __device__ __forceinline__ unsigned xb_add(unsigned* p, unsigned v) { return __hip_atomic_fetch_add(p, v, __ATOMIC_RELAXED, __HIP_MEMORY_SCOPE_AGENT); }
; #define XB_SPIN(cond, bar) do { unsigned _sp = 0; while (cond) { __builtin_amdgcn_s_sleep(1); \
;     if ((++_sp & 255u) == 0u) { if (xb_ld(&(bar)[XB_TMO])) break; if (_sp > XB_SPIN_CAP) { atomicAdd(&(bar)[XB_TMO], 1u); break; } } } } while (0)
; __device__ __forceinline__ void xcd_barrier(const XcdBarrier& b) {
;     ...
;         if (old + 1u == (gen + 1u) * nloc) {
;             __builtin_amdgcn_fence(__ATOMIC_RELEASE, "agent");
;             asm volatile("s_waitcnt vmcnt(0)" ::: "memory");
;             const unsigned og = xb_add(&bar[XB_TOP], 1u);
;             const unsigned tg = og / nx;
;             if (og + 1u == (tg + 1u) * nx) xb_add(&bar[XB_TOPGEN], 1u);
;             else XB_SPIN(xb_ld(&bar[XB_TOPGEN]) == tg, bar);
.LBB0_92:
	s_andn2_saveexec_b64 s[6:7], s[10:11]
	s_cbranch_execz .LBB0_112
	s_mov_b64 s[10:11], exec
	buffer_wbl2 sc1
	s_waitcnt lgkmcnt(0)
	s_waitcnt vmcnt(0)
	buffer_inv sc1
	v_mbcnt_lo_u32_b32 v1, s10, 0
	v_mbcnt_hi_u32_b32 v1, s11, v1
	v_cmp_eq_u32_e32 vcc, 0, v1
	s_and_saveexec_b64 s[12:13], vcc
	s_cbranch_execz .LBB0_95
	s_bcnt1_i32_b64 s3, s[10:11]
	v_mov_b32_e32 v2, 0x53000
	v_mov_b32_e32 v3, s3
	global_atomic_add v2, v2, v3, s[70:71] offset:1024 sc0

; __device__ __forceinline__ unsigned xb_add(unsigned* p, unsigned v) { return __hip_atomic_fetch_add(p, v, __ATOMIC_RELAXED, __HIP_MEMORY_SCOPE_AGENT); }
; __device__ __forceinline__ void xcd_barrier(const XcdBarrier& b) {
;     ...
;             __builtin_amdgcn_fence(__ATOMIC_ACQUIRE, "agent");
;             xb_add(&bar[XB_XGEN(b.x)], 1u);
;             asm volatile("s_waitcnt vmcnt(0)" ::: "memory");
.LBB0_109:
	s_or_b64 exec, exec, s[10:11]
	s_mov_b64 s[10:11], exec
	v_mbcnt_lo_u32_b32 v0, s10, 0
	v_mbcnt_hi_u32_b32 v0, s11, v0
	v_cmp_eq_u32_e32 vcc, 0, v0
	s_waitcnt vmcnt(0)
	s_and_saveexec_b64 s[12:13], vcc
	s_cbranch_execz .LBB0_111
	s_bcnt1_i32_b64 s3, s[10:11]
	v_mov_b32_e32 v0, 0x2000
	v_mov_b32_e32 v1, s3
	global_atomic_add v0, v1, s[8:9] offset:1024

; __device__ __forceinline__ unsigned xb_ld(unsigned* p)              { return __hip_atomic_load(p, __ATOMIC_RELAXED, __HIP_MEMORY_SCOPE_AGENT); }
; __device__ __forceinline__ unsigned xb_add(unsigned* p, unsigned v) { return __hip_atomic_fetch_add(p, v, __ATOMIC_RELAXED, __HIP_MEMORY_SCOPE_AGENT); }
; #define XB_SPIN(cond, bar) do { unsigned _sp = 0; while (cond) { __builtin_amdgcn_s_sleep(1); \
;     if ((++_sp & 255u) == 0u) { if (xb_ld(&(bar)[XB_TMO])) break; if (_sp > XB_SPIN_CAP) { atomicAdd(&(bar)[XB_TMO], 1u); break; } } } } while (0)
; __device__ __forceinline__ void xcd_barrier(const XcdBarrier& b) {
;     ...
;         if (old + 1u == (gen + 1u) * nloc) {
;             __builtin_amdgcn_fence(__ATOMIC_RELEASE, "agent");
;             asm volatile("s_waitcnt vmcnt(0)" ::: "memory");
;             const unsigned og = xb_add(&bar[XB_TOP], 1u);
;             const unsigned tg = og / nx;
;             if (og + 1u == (tg + 1u) * nx) xb_add(&bar[XB_TOPGEN], 1u);
;             else XB_SPIN(xb_ld(&bar[XB_TOPGEN]) == tg, bar);
.LBB0_178:
	s_andn2_saveexec_b64 s[6:7], s[10:11]
	s_cbranch_execz .LBB0_198
	s_mov_b64 s[10:11], exec
	buffer_wbl2 sc1
	s_waitcnt lgkmcnt(0)
	s_waitcnt vmcnt(0)
	buffer_inv sc1
	v_mbcnt_lo_u32_b32 v1, s10, 0
	v_mbcnt_hi_u32_b32 v1, s11, v1
	v_cmp_eq_u32_e32 vcc, 0, v1
	s_and_saveexec_b64 s[30:31], vcc
	s_cbranch_execz .LBB0_181
	s_bcnt1_i32_b64 s3, s[10:11]
	v_mov_b32_e32 v2, 0x53000
	v_mov_b32_e32 v3, s3
	global_atomic_add v2, v2, v3, s[70:71] offset:1024 sc0

; __device__ __forceinline__ unsigned xb_add(unsigned* p, unsigned v) { return __hip_atomic_fetch_add(p, v, __ATOMIC_RELAXED, __HIP_MEMORY_SCOPE_AGENT); }
; __device__ __forceinline__ void xcd_barrier(const XcdBarrier& b) {
;     ...
;             __builtin_amdgcn_fence(__ATOMIC_ACQUIRE, "agent");
;             xb_add(&bar[XB_XGEN(b.x)], 1u);
;             asm volatile("s_waitcnt vmcnt(0)" ::: "memory");
.LBB0_195:
	s_or_b64 exec, exec, s[10:11]
	s_mov_b64 s[10:11], exec
	v_mbcnt_lo_u32_b32 v0, s10, 0
	v_mbcnt_hi_u32_b32 v0, s11, v0
	v_cmp_eq_u32_e32 vcc, 0, v0
	s_waitcnt vmcnt(0)
	s_and_saveexec_b64 s[30:31], vcc
	s_cbranch_execz .LBB0_197
	s_bcnt1_i32_b64 s3, s[10:11]
	v_mov_b32_e32 v0, 0x2000
	v_mov_b32_e32 v1, s3
	global_atomic_add v0, v1, s[8:9] offset:1024

; __device__ __forceinline__ unsigned xb_ld(unsigned* p)              { return __hip_atomic_load(p, __ATOMIC_RELAXED, __HIP_MEMORY_SCOPE_AGENT); }
; __device__ __forceinline__ unsigned xb_add(unsigned* p, unsigned v) { return __hip_atomic_fetch_add(p, v, __ATOMIC_RELAXED, __HIP_MEMORY_SCOPE_AGENT); }
; #define XB_SPIN(cond, bar) do { unsigned _sp = 0; while (cond) { __builtin_amdgcn_s_sleep(1); \
;     if ((++_sp & 255u) == 0u) { if (xb_ld(&(bar)[XB_TMO])) break; if (_sp > XB_SPIN_CAP) { atomicAdd(&(bar)[XB_TMO], 1u); break; } } } } while (0)
; __device__ __forceinline__ void xcd_barrier(const XcdBarrier& b) {
;     ...
;         if (old + 1u == (gen + 1u) * nloc) {
;             __builtin_amdgcn_fence(__ATOMIC_RELEASE, "agent");
;             asm volatile("s_waitcnt vmcnt(0)" ::: "memory");
;             const unsigned og = xb_add(&bar[XB_TOP], 1u);
;             const unsigned tg = og / nx;
;             if (og + 1u == (tg + 1u) * nx) xb_add(&bar[XB_TOPGEN], 1u);
;             else XB_SPIN(xb_ld(&bar[XB_TOPGEN]) == tg, bar);
.LBB0_234:
	s_andn2_saveexec_b64 s[6:7], s[8:9]
	s_cbranch_execz .LBB0_254
	s_mov_b64 s[8:9], exec
	buffer_wbl2 sc1
	s_waitcnt lgkmcnt(0)
	s_waitcnt vmcnt(0)
	buffer_inv sc1
	v_mbcnt_lo_u32_b32 v1, s8, 0
	v_mbcnt_hi_u32_b32 v1, s9, v1
	v_cmp_eq_u32_e32 vcc, 0, v1
	s_and_saveexec_b64 s[10:11], vcc
	s_cbranch_execz .LBB0_237
	s_bcnt1_i32_b64 s3, s[8:9]
	v_mov_b32_e32 v2, 0x53000
	v_mov_b32_e32 v3, s3
	global_atomic_add v2, v2, v3, s[70:71] offset:1024 sc0

; __device__ __forceinline__ unsigned xb_add(unsigned* p, unsigned v) { return __hip_atomic_fetch_add(p, v, __ATOMIC_RELAXED, __HIP_MEMORY_SCOPE_AGENT); }
; __device__ __forceinline__ void xcd_barrier(const XcdBarrier& b) {
;     ...
;             __builtin_amdgcn_fence(__ATOMIC_ACQUIRE, "agent");
;             xb_add(&bar[XB_XGEN(b.x)], 1u);
;             asm volatile("s_waitcnt vmcnt(0)" ::: "memory");
.LBB0_251:
	s_or_b64 exec, exec, s[8:9]
	s_mov_b64 s[8:9], exec
	v_mbcnt_lo_u32_b32 v0, s8, 0
	v_mbcnt_hi_u32_b32 v0, s9, v0
	v_cmp_eq_u32_e32 vcc, 0, v0
	s_waitcnt vmcnt(0)
	s_and_saveexec_b64 s[10:11], vcc
	s_cbranch_execz .LBB0_253
	s_bcnt1_i32_b64 s3, s[8:9]
	v_mov_b32_e32 v0, 0x2000
	v_mov_b32_e32 v1, s3
	global_atomic_add v0, v1, s[4:5] offset:1024

; __device__ __forceinline__ unsigned xb_ld(unsigned* p)              { return __hip_atomic_load(p, __ATOMIC_RELAXED, __HIP_MEMORY_SCOPE_AGENT); }
; __device__ __forceinline__ unsigned xb_add(unsigned* p, unsigned v) { return __hip_atomic_fetch_add(p, v, __ATOMIC_RELAXED, __HIP_MEMORY_SCOPE_AGENT); }
; #define XB_SPIN(cond, bar) do { unsigned _sp = 0; while (cond) { __builtin_amdgcn_s_sleep(1); \
;     if ((++_sp & 255u) == 0u) { if (xb_ld(&(bar)[XB_TMO])) break; if (_sp > XB_SPIN_CAP) { atomicAdd(&(bar)[XB_TMO], 1u); break; } } } } while (0)
; __device__ __forceinline__ void xcd_barrier(const XcdBarrier& b) {
;     ...
;         if (old + 1u == (gen + 1u) * nloc) {
;             __builtin_amdgcn_fence(__ATOMIC_RELEASE, "agent");
;             asm volatile("s_waitcnt vmcnt(0)" ::: "memory");
;             const unsigned og = xb_add(&bar[XB_TOP], 1u);
;             const unsigned tg = og / nx;
;             if (og + 1u == (tg + 1u) * nx) xb_add(&bar[XB_TOPGEN], 1u);
;             else XB_SPIN(xb_ld(&bar[XB_TOPGEN]) == tg, bar);
.LBB0_770:
	s_andn2_saveexec_b64 s[6:7], s[8:9]
	s_cbranch_execz .LBB0_790
	s_mov_b64 s[8:9], exec
	buffer_wbl2 sc1
	s_waitcnt lgkmcnt(0)
	s_waitcnt vmcnt(0)
	buffer_inv sc1
	v_mbcnt_lo_u32_b32 v1, s8, 0
	v_mbcnt_hi_u32_b32 v1, s9, v1
	v_cmp_eq_u32_e32 vcc, 0, v1
	s_and_saveexec_b64 s[10:11], vcc
	s_cbranch_execz .LBB0_773
	s_bcnt1_i32_b64 s2, s[8:9]
	v_mov_b32_e32 v2, 0x53000
	v_mov_b32_e32 v3, s2
	global_atomic_add v2, v2, v3, s[70:71] offset:1024 sc0

; __device__ __forceinline__ unsigned xb_add(unsigned* p, unsigned v) { return __hip_atomic_fetch_add(p, v, __ATOMIC_RELAXED, __HIP_MEMORY_SCOPE_AGENT); }
; __device__ __forceinline__ void xcd_barrier(const XcdBarrier& b) {
;     ...
;             __builtin_amdgcn_fence(__ATOMIC_ACQUIRE, "agent");
;             xb_add(&bar[XB_XGEN(b.x)], 1u);
;             asm volatile("s_waitcnt vmcnt(0)" ::: "memory");
.LBB0_787:
	s_or_b64 exec, exec, s[8:9]
	s_mov_b64 s[8:9], exec
	v_mbcnt_lo_u32_b32 v0, s8, 0
	v_mbcnt_hi_u32_b32 v0, s9, v0
	v_cmp_eq_u32_e32 vcc, 0, v0
	s_waitcnt vmcnt(0)
	s_and_saveexec_b64 s[10:11], vcc
	s_cbranch_execz .LBB0_789
	s_bcnt1_i32_b64 s2, s[8:9]
	v_mov_b32_e32 v0, 0x2000
	v_mov_b32_e32 v1, s2
	global_atomic_add v0, v1, s[4:5] offset:1024

; __device__ __forceinline__ unsigned xb_ld(unsigned* p)              { return __hip_atomic_load(p, __ATOMIC_RELAXED, __HIP_MEMORY_SCOPE_AGENT); }
; __device__ __forceinline__ unsigned xb_add(unsigned* p, unsigned v) { return __hip_atomic_fetch_add(p, v, __ATOMIC_RELAXED, __HIP_MEMORY_SCOPE_AGENT); }
; #define XB_SPIN(cond, bar) do { unsigned _sp = 0; while (cond) { __builtin_amdgcn_s_sleep(1); \
;     if ((++_sp & 255u) == 0u) { if (xb_ld(&(bar)[XB_TMO])) break; if (_sp > XB_SPIN_CAP) { atomicAdd(&(bar)[XB_TMO], 1u); break; } } } } while (0)
; __device__ __forceinline__ void xcd_barrier(const XcdBarrier& b) {
;     ...
;         if (old + 1u == (gen + 1u) * nloc) {
;             __builtin_amdgcn_fence(__ATOMIC_RELEASE, "agent");
;             asm volatile("s_waitcnt vmcnt(0)" ::: "memory");
;             const unsigned og = xb_add(&bar[XB_TOP], 1u);
;             const unsigned tg = og / nx;
;             if (og + 1u == (tg + 1u) * nx) xb_add(&bar[XB_TOPGEN], 1u);
;             else XB_SPIN(xb_ld(&bar[XB_TOPGEN]) == tg, bar);
.LBB0_1242:
	s_andn2_saveexec_b64 s[6:7], s[10:11]
	s_cbranch_execz .LBB0_1262
	s_mov_b64 s[10:11], exec
	buffer_wbl2 sc1
	s_waitcnt lgkmcnt(0)
	s_waitcnt vmcnt(0)
	buffer_inv sc1
	v_mbcnt_lo_u32_b32 v1, s10, 0
	v_mbcnt_hi_u32_b32 v1, s11, v1
	v_cmp_eq_u32_e32 vcc, 0, v1
	s_and_saveexec_b64 s[30:31], vcc
	s_cbranch_execz .LBB0_1245
	s_bcnt1_i32_b64 s2, s[10:11]
	v_mov_b32_e32 v2, 0x53000
	v_mov_b32_e32 v3, s2
	global_atomic_add v2, v2, v3, s[70:71] offset:1024 sc0

; __device__ __forceinline__ unsigned xb_add(unsigned* p, unsigned v) { return __hip_atomic_fetch_add(p, v, __ATOMIC_RELAXED, __HIP_MEMORY_SCOPE_AGENT); }
; __device__ __forceinline__ void xcd_barrier(const XcdBarrier& b) {
;     ...
;             __builtin_amdgcn_fence(__ATOMIC_ACQUIRE, "agent");
;             xb_add(&bar[XB_XGEN(b.x)], 1u);
;             asm volatile("s_waitcnt vmcnt(0)" ::: "memory");
.LBB0_1259:
	s_or_b64 exec, exec, s[10:11]
	s_mov_b64 s[10:11], exec
	v_mbcnt_lo_u32_b32 v0, s10, 0
	v_mbcnt_hi_u32_b32 v0, s11, v0
	v_cmp_eq_u32_e32 vcc, 0, v0
	s_waitcnt vmcnt(0)
	s_and_saveexec_b64 s[30:31], vcc
	s_cbranch_execz .LBB0_1261
	s_bcnt1_i32_b64 s2, s[10:11]
	v_mov_b32_e32 v0, 0x2000
	v_mov_b32_e32 v1, s2
	global_atomic_add v0, v1, s[8:9] offset:1024

; __device__ __forceinline__ unsigned xb_ld(unsigned* p)              { return __hip_atomic_load(p, __ATOMIC_RELAXED, __HIP_MEMORY_SCOPE_AGENT); }
; __device__ __forceinline__ unsigned xb_add(unsigned* p, unsigned v) { return __hip_atomic_fetch_add(p, v, __ATOMIC_RELAXED, __HIP_MEMORY_SCOPE_AGENT); }
; #define XB_SPIN(cond, bar) do { unsigned _sp = 0; while (cond) { __builtin_amdgcn_s_sleep(1); \
;     if ((++_sp & 255u) == 0u) { if (xb_ld(&(bar)[XB_TMO])) break; if (_sp > XB_SPIN_CAP) { atomicAdd(&(bar)[XB_TMO], 1u); break; } } } } while (0)
; __device__ __forceinline__ void xcd_barrier(const XcdBarrier& b) {
;     ...
;         if (old + 1u == (gen + 1u) * nloc) {
;             __builtin_amdgcn_fence(__ATOMIC_RELEASE, "agent");
;             asm volatile("s_waitcnt vmcnt(0)" ::: "memory");
;             const unsigned og = xb_add(&bar[XB_TOP], 1u);
;             const unsigned tg = og / nx;
;             if (og + 1u == (tg + 1u) * nx) xb_add(&bar[XB_TOPGEN], 1u);
;             else XB_SPIN(xb_ld(&bar[XB_TOPGEN]) == tg, bar);
.LBB0_2091:
	s_andn2_saveexec_b64 s[4:5], s[4:5]
	s_cbranch_execz .LBB0_2111
	s_mov_b64 s[4:5], exec
	buffer_wbl2 sc1
	s_waitcnt lgkmcnt(0)
	s_waitcnt vmcnt(0)
	buffer_inv sc1
	v_mbcnt_lo_u32_b32 v1, s4, 0
	v_mbcnt_hi_u32_b32 v1, s5, v1
	v_cmp_eq_u32_e32 vcc, 0, v1
	s_and_saveexec_b64 s[6:7], vcc
	s_cbranch_execz .LBB0_2094
	s_bcnt1_i32_b64 s4, s[4:5]
	v_mov_b32_e32 v2, 0x53000
	v_mov_b32_e32 v3, s4
	global_atomic_add v2, v2, v3, s[70:71] offset:1024 sc0

; __device__ __forceinline__ unsigned xb_add(unsigned* p, unsigned v) { return __hip_atomic_fetch_add(p, v, __ATOMIC_RELAXED, __HIP_MEMORY_SCOPE_AGENT); }
; __device__ __forceinline__ void xcd_barrier(const XcdBarrier& b) {
;     ...
;             __builtin_amdgcn_fence(__ATOMIC_ACQUIRE, "agent");
;             xb_add(&bar[XB_XGEN(b.x)], 1u);
;             asm volatile("s_waitcnt vmcnt(0)" ::: "memory");
.LBB0_2108:
	s_or_b64 exec, exec, s[4:5]
	s_mov_b64 s[4:5], exec
	v_mbcnt_lo_u32_b32 v0, s4, 0
	v_mbcnt_hi_u32_b32 v0, s5, v0
	v_cmp_eq_u32_e32 vcc, 0, v0
	s_waitcnt vmcnt(0)
	s_and_saveexec_b64 s[6:7], vcc
	s_cbranch_execz .LBB0_2110
	s_bcnt1_i32_b64 s4, s[4:5]
	v_mov_b32_e32 v0, 0x2000
	v_mov_b32_e32 v1, s4
	global_atomic_add v0, v1, s[2:3] offset:1024
